# MLA sample attention: K rows double-buffered in landing registers so next-tile K loads overlap the per-tile RMS norm (both unit copies)
# baseline (speedup 1.0000x reference)
.LBB0_654:
	s_or_b64 exec, exec, s[0:1]
	v_lshl_add_u32 v1, v122, 2, 0
	v_add_u32_e32 v2, 0x10000, v1
	s_waitcnt lgkmcnt(0)
	s_barrier
	ds_read2_b32 v[14:15], v2 offset1:32
	ds_read2_b32 v[16:17], v2 offset0:64 offset1:96
	ds_read2_b32 v[18:19], v2 offset0:128 offset1:160
	ds_read2_b32 v[20:21], v2 offset0:192 offset1:224
	v_mov_b32_e32 v2, 0xf149f2ca
	s_waitcnt lgkmcnt(3)
	v_max3_f32 v3, v14, v2, v15
	s_waitcnt lgkmcnt(2)
	v_max3_f32 v3, v3, v16, v17
	s_lshl_b64 s[0:1], s[16:17], 13
	s_waitcnt lgkmcnt(1)
	v_max3_f32 v3, v3, v18, v19
	v_lshlrev_b32_e32 v5, 9, v122
	v_lshlrev_b32_e32 v6, 2, v120
	s_add_u32 s15, s36, s0
	s_waitcnt lgkmcnt(0)
	v_max3_f32 v3, v3, v20, v21
	v_add3_u32 v5, 0, v5, v6
	s_addc_u32 s20, s37, s1
	v_sub_f32_e32 v10, v14, v3
	ds_read_b128 v[6:9], v5
	s_add_u32 s21, s38, s0
	v_exp_f32_e32 v14, v10
	s_addc_u32 s22, s39, s1
	s_add_u32 s18, s15, s2
	s_addc_u32 s19, s20, 0
	ds_read_b128 v[10:13], v5 offset:8192
	s_waitcnt lgkmcnt(1)
	v_pk_fma_f32 v[24:25], v[6:7], v[14:15], 0 op_sel_hi:[1,0,0]
	v_lshl_add_u64 v[6:7], s[18:19], 0, v[118:119]
	v_lshlrev_b32_e32 v26, 1, v120
	v_mov_b32_e32 v27, v4
	v_lshl_add_u64 v[6:7], v[6:7], 0, v[26:27]
	global_load_dwordx2 v[28:29], v[6:7], off
	v_pk_fma_f32 v[22:23], v[8:9], v[14:15], 0 op_sel_hi:[1,0,0]
	v_sub_f32_e32 v8, v15, v3
	v_exp_f32_e32 v30, v8
	v_add_u32_e32 v32, 0x10040, v1
	v_add_u32_e32 v6, 0x100c0, v1
	v_add_u32_e32 v33, 0x10240, v1
	v_add_u32_e32 v34, 0x102c0, v1
	v_add_u32_e32 v35, 0x10340, v1
	v_mov_b32_e32 v31, v14
	v_add_u32_e32 v8, 0x10140, v1
	v_add_u32_e32 v9, 0x101c0, v1
	v_add_u32_e32 v1, 0x103c0, v1
	ds_read_b32 v7, v32
	ds_read_b32 v6, v6
	ds_read_b32 v14, v8
	ds_read_b32 v15, v9
	ds_read_b32 v32, v33
	ds_read_b32 v33, v34
	ds_read_b32 v34, v35
	ds_read_b32 v35, v1
	s_waitcnt lgkmcnt(6)
	v_pk_mul_f32 v[36:37], v[6:7], v[30:31]
	v_sub_f32_e32 v1, v16, v3
	ds_read_b128 v[6:9], v5 offset:16384
	v_exp_f32_e32 v16, v1
	v_pk_fma_f32 v[22:23], v[12:13], v[30:31], v[22:23] op_sel_hi:[1,0,1]
	v_pk_fma_f32 v[24:25], v[10:11], v[30:31], v[24:25] op_sel_hi:[1,0,1]
	v_sub_f32_e32 v1, v17, v3
	ds_read_b128 v[10:13], v5 offset:24576
	s_waitcnt lgkmcnt(1)
	v_pk_fma_f32 v[24:25], v[16:17], v[6:7], v[24:25] op_sel_hi:[0,1,1]
	v_pk_fma_f32 v[22:23], v[16:17], v[8:9], v[22:23] op_sel_hi:[0,1,1]
	v_exp_f32_e32 v17, v1
	v_sub_f32_e32 v18, v18, v3
	ds_read_b128 v[6:9], v5 offset:32768
	v_exp_f32_e32 v18, v18
	v_mov_b32_e32 v30, v17
	s_waitcnt lgkmcnt(1)
	v_pk_fma_f32 v[24:25], v[30:31], v[10:11], v[24:25] op_sel_hi:[0,1,1]
	v_add_f32_e32 v1, 0, v37
	v_pk_fma_f32 v[22:23], v[30:31], v[12:13], v[22:23] op_sel_hi:[0,1,1]
	ds_read_b128 v[10:13], v5 offset:40960
	s_waitcnt lgkmcnt(1)
	v_pk_fma_f32 v[24:25], v[18:19], v[6:7], v[24:25] op_sel_hi:[0,1,1]
	v_sub_f32_e32 v6, v19, v3
	v_add_f32_e32 v1, v36, v1
	v_pk_fma_f32 v[22:23], v[18:19], v[8:9], v[22:23] op_sel_hi:[0,1,1]
	v_exp_f32_e32 v19, v6
	v_pk_mul_f32 v[6:7], v[16:17], v[14:15]
	v_sub_f32_e32 v15, v20, v3
	v_add_f32_e32 v1, v1, v6
	v_add_f32_e32 v1, v1, v7
	ds_read_b128 v[6:9], v5 offset:49152
	v_exp_f32_e32 v16, v15
	v_mov_b32_e32 v14, v19
	s_waitcnt lgkmcnt(1)
	v_pk_fma_f32 v[22:23], v[14:15], v[12:13], v[22:23] op_sel_hi:[0,1,1]
	v_pk_fma_f32 v[14:15], v[14:15], v[10:11], v[24:25] op_sel_hi:[0,1,1]
	v_sub_f32_e32 v3, v21, v3
	ds_read_b128 v[10:13], v5 offset:57344
	s_waitcnt lgkmcnt(1)
	v_pk_fma_f32 v[6:7], v[16:17], v[6:7], v[14:15] op_sel_hi:[0,1,1]
	v_pk_fma_f32 v[8:9], v[16:17], v[8:9], v[22:23] op_sel_hi:[0,1,1]
	v_exp_f32_e32 v17, v3
	v_pk_mul_f32 v[14:15], v[18:19], v[32:33]
	s_add_u32 s0, s21, s2
	v_add_f32_e32 v1, v1, v14
	v_add_f32_e32 v1, v1, v15
	v_pk_mul_f32 v[14:15], v[16:17], v[34:35]
	s_addc_u32 s1, s22, 0
	v_add_f32_e32 v1, v1, v14
	v_add_f32_e32 v1, v1, v15
	v_div_scale_f32 v3, s[18:19], v1, v1, 1.0
	v_rcp_f32_e32 v5, v3
	v_mov_b32_e32 v14, v17
	s_waitcnt lgkmcnt(0)
	v_pk_fma_f32 v[6:7], v[14:15], v[10:11], v[6:7] op_sel_hi:[0,1,1]
	v_pk_fma_f32 v[8:9], v[14:15], v[12:13], v[8:9] op_sel_hi:[0,1,1]
	v_fma_f32 v10, -v3, v5, 1.0
	v_fmac_f32_e32 v5, v10, v5
	v_div_scale_f32 v10, vcc, 1.0, v1, 1.0
	v_mul_f32_e32 v11, v10, v5
	v_fma_f32 v12, -v3, v11, v10
	v_fmac_f32_e32 v11, v12, v5
	v_fma_f32 v3, -v3, v11, v10
	v_div_fmas_f32 v3, v3, v5, v11
	v_div_fixup_f32 v1, v3, v1, 1.0
	v_mul_f32_e32 v6, v1, v6
	v_readlane_b32 s18, v254, 28
	v_readlane_b32 s19, v254, 29
	v_mov_b32_e32 v71, v4
	s_waitcnt vmcnt(0)
	v_lshlrev_b32_e32 v3, 16, v28
	v_and_b32_e32 v5, 0xffff0000, v28
	v_mul_f32_e32 v3, v6, v3
	v_mul_f32_e32 v6, v1, v7
	v_mul_f32_e32 v5, v6, v5
	v_cvt_pk_bf16_f32 v6, v3, v5
	v_mul_f32_e32 v3, v1, v8
	v_mul_f32_e32 v1, v1, v9
	v_lshl_add_u64 v[8:9], s[0:1], 0, v[118:119]
	s_mul_i32 s0, s17, 0x1800
	s_mul_hi_u32 s1, s16, 0x1800
	s_add_i32 s1, s1, s0
	s_mul_i32 s0, s16, 0x1800
	s_add_u32 s0, s40, s0
	s_addc_u32 s1, s41, s1
	s_mul_i32 s16, s18, 0x180
	v_and_b32_e32 v11, 0xffff0000, v29
	s_add_u32 s16, s0, s16
	v_lshlrev_b32_e32 v10, 16, v29
	v_mul_f32_e32 v1, v1, v11
	s_addc_u32 s17, s1, 0
	s_mul_i32 s1, s14, 0x1020000
	v_mul_f32_e32 v3, v3, v10
	v_cvt_pk_bf16_f32 v7, v3, v1
	v_lshl_add_u64 v[8:9], v[8:9], 0, v[26:27]
	s_mul_hi_i32 s0, s14, 0x1020000
	s_add_u32 s1, s42, s1
	v_mov_b32_e32 v1, v0
	global_store_dwordx2 v[8:9], v[6:7], off
	s_barrier
	s_addc_u32 s0, s43, s0
	s_lshl_b32 s18, s18, 9
	s_add_u32 s18, s1, s18
	v_ashrrev_i32_e32 v74, 4, v1
	v_and_b32_e32 v116, 15, v1
	v_min_i32_e32 v46, 0x7ef, v74
	s_addc_u32 s19, s0, 0
	v_lshlrev_b32_e32 v70, 4, v116
	v_ashrrev_i32_e32 v47, 31, v46
	v_mul_u32_u24_e32 v6, 0x1800, v116
	v_mov_b32_e32 v7, v4
	v_lshl_add_u64 v[112:113], s[18:19], 0, v[70:71]
	v_lshlrev_b64 v[46:47], 13, v[46:47]
	v_min_i32_e32 v50, 0x7cf, v74
	v_lshl_add_u64 v[6:7], s[16:17], 0, v[6:7]
	v_lshl_add_u64 v[46:47], v[112:113], 0, v[46:47]
	s_mov_b32 s16, 0x40000
	v_ashrrev_i32_e32 v51, 31, v50
	v_lshl_add_u64 v[48:49], v[46:47], 0, s[4:5]
	v_add_co_u32_e32 v46, vcc, s16, v46
	v_lshlrev_b64 v[50:51], 13, v[50:51]
	v_min_i32_e32 v54, 0x7af, v74
	s_mul_i32 s0, s14, 0x40800
	v_bfe_u32 v117, v1, 4, 2
	v_ashrrev_i32_e32 v75, 3, v1
	v_addc_co_u32_e32 v47, vcc, 0, v47, vcc
	v_lshl_add_u64 v[50:51], v[112:113], 0, v[50:51]
	s_mov_b32 s18, 0x80000
	v_ashrrev_i32_e32 v55, 31, v54
	s_mul_hi_i32 s1, s14, 0x40800
	s_add_u32 s0, s44, s0
	v_lshlrev_b32_e32 v110, 4, v117
	v_mov_b32_e32 v111, v4
	v_lshl_add_u64 v[52:53], v[50:51], 0, s[96:97]
	v_add_co_u32_e32 v50, vcc, s18, v50
	v_lshlrev_b64 v[54:55], 13, v[54:55]
	v_lshlrev_b32_e32 v58, 4, v1
	v_min_i32_e32 v60, 0x7cf, v75
	s_addc_u32 s1, s45, s1
	v_lshl_add_u64 v[26:27], v[6:7], 0, v[110:111]
	v_addc_co_u32_e32 v51, vcc, 0, v51, vcc
	v_lshl_add_u64 v[54:55], v[112:113], 0, v[54:55]
	s_mov_b64 s[24:25], 0xc0000
	v_and_b32_e32 v58, 0x70, v58
	v_mov_b32_e32 v59, v4
	v_ashrrev_i32_e32 v61, 31, v60
	global_load_dwordx4 v[6:9], v[26:27], off
	global_load_dwordx4 v[10:13], v[26:27], off offset:64
	global_load_dwordx4 v[14:17], v[26:27], off offset:128
	global_load_dwordx4 v[18:21], v[26:27], off offset:192
	global_load_dwordx4 v[22:25], v[26:27], off offset:256
	s_nop 0
	global_load_dwordx4 v[26:29], v[26:27], off offset:320
	v_min_i32_e32 v38, 0x80f, v74
	v_lshl_add_u64 v[56:57], v[54:55], 0, s[24:25]
	v_add_co_u32_e32 v54, vcc, s48, v54
	v_lshl_add_u64 v[114:115], s[0:1], 0, v[58:59]
	v_min_i32_e32 v58, 0x80f, v75
	v_lshlrev_b64 v[60:61], 7, v[60:61]
	v_bfe_u32 v30, v1, 1, 1
	v_and_b32_e32 v31, 12, v1
	v_ashrrev_i32_e32 v39, 31, v38
	v_addc_co_u32_e32 v55, vcc, 0, v55, vcc
	v_ashrrev_i32_e32 v59, 31, v58
	v_lshl_add_u64 v[60:61], v[114:115], 0, v[60:61]
	v_bitop3_b32 v30, v117, v30, v31 bitop3:0x36
	v_lshlrev_b64 v[38:39], 13, v[38:39]
	v_lshlrev_b64 v[58:59], 7, v[58:59]
	v_add_co_u32_e32 v66, vcc, s88, v60
	v_lshlrev_b32_e32 v72, 4, v30
	v_lshlrev_b32_e32 v30, 3, v1
	v_lshlrev_b32_e32 v34, 5, v116
	v_lshl_add_u64 v[38:39], v[112:113], 0, v[38:39]
	v_lshl_add_u64 v[58:59], v[114:115], 0, v[58:59]
	v_addc_co_u32_e32 v67, vcc, 0, v61, vcc
	v_and_or_b32 v73, v30, 8, s3
	global_load_dwordx4 v[30:33], v34, s[12:13]
	s_nop 0
	global_load_dwordx4 v[34:37], v34, s[12:13] offset:16
	s_nop 0
	global_load_dwordx4 v[186:189], v[38:39], off nt
	s_nop 0
	global_load_dwordx4 v[190:193], v[46:47], off nt
	s_nop 0
	global_load_dwordx4 v[194:197], v[50:51], off nt
	s_nop 0
	global_load_dwordx4 v[198:201], v[54:55], off nt
	s_nop 0
	global_load_dwordx4 v[38:41], v[38:39], off offset:256 nt
	s_nop 0
	global_load_dwordx4 v[46:49], v[48:49], off offset:256 nt
	s_nop 0
	global_load_dwordx4 v[50:53], v[52:53], off offset:256 nt
	s_nop 0
	global_load_dwordx4 v[54:57], v[56:57], off offset:256 nt
	s_nop 0
	global_load_dwordx4 v[58:61], v[58:59], off
	s_nop 0
	global_load_dwordx4 v[66:69], v[66:67], off
	v_readfirstlane_b32 s14, v1
	s_ashr_i32 s14, s14, 6
	v_lshlrev_b32_e32 v76, 2, v74
	s_lshl_b32 s17, s14, 4
	v_bfe_u32 v3, v1, 2, 2
	v_lshlrev_b32_e32 v5, 2, v117
	v_and_b32_e32 v76, 12, v76
	v_bfe_u32 v77, v74, 2, 2
	s_movk_i32 s0, 0x70
	v_bitop3_b32 v76, v76, v116, v77 bitop3:0x36
	v_xor_b32_e32 v77, v75, v1
	v_or3_b32 v3, v3, v5, s17
	s_movk_i32 s1, 0x180
	v_bitop3_b32 v71, v70, v1, s0 bitop3:0x78
	v_lshlrev_b32_e32 v77, 4, v77
	v_or_b32_e32 v78, s17, v116
	v_lshlrev_b32_e32 v3, 8, v3
	v_mul_lo_u32 v80, v75, s1
	v_and_b32_e32 v81, 0x70, v70
	v_bitop3_b32 v70, v110, v70, s0 bitop3:0x78
	s_movk_i32 s0, 0x80
	v_mul_lo_u32 v79, v74, s1
	v_add3_u32 v111, v73, v72, v3
	v_and_b32_e32 v72, 0x70, v77
	v_add_u32_e32 v77, 0, v80
	v_mul_lo_u32 v78, v78, s1
	v_bitop3_b32 v80, v110, v81, s0 bitop3:0x36
	s_movk_i32 s0, 0x140
	v_mov_b32_e32 v120, 0
	v_lshlrev_b32_e32 v3, 8, v74
	v_add_u32_e32 v73, 0, v79
	v_lshl_add_u32 v76, v76, 4, s3
	v_add_u32_e32 v78, 0, v78
	v_bitop3_b32 v79, v110, v81, 64 bitop3:0x36
	v_bitop3_b32 v82, v110, v81, s87 bitop3:0x36
	v_bitop3_b32 v83, v110, v81, s92 bitop3:0x36
	v_bitop3_b32 v81, v110, v81, s0 bitop3:0x36
	s_mov_b32 s16, 0
	v_xor_b32_e32 v118, 32, v111
	v_xor_b32_e32 v119, 64, v111
	v_xor_b32_e32 v121, 0x60, v111
	v_xor_b32_e32 v122, 0x80, v111
	v_xor_b32_e32 v123, 0xa0, v111
	v_xor_b32_e32 v124, 0xc0, v111
	v_xor_b32_e32 v125, 0xe0, v111
	v_or_b32_e32 v126, s17, v5
	v_add_u32_e32 v127, 0x80, v75
	v_add_u32_e32 v128, 0x80, v74
	v_add_u32_e32 v129, v73, v71
	v_add_u32_e32 v130, v76, v3
	v_add_u32_e32 v131, v77, v72
	v_add_u32_e32 v132, v78, v70
	v_add_u32_e32 v133, v78, v79
	v_add_u32_e32 v134, v78, v80
	v_add_u32_e32 v135, v78, v82
	v_add_u32_e32 v136, v78, v83
	v_add_u32_e32 v137, v78, v81
	v_mov_b32_e32 v70, 0
	v_mov_b32_e32 v71, v120
	v_mov_b32_e32 v72, v120
	v_mov_b32_e32 v73, v120
	v_mov_b32_e32 v74, 0
	v_mov_b32_e32 v75, v120
	v_mov_b32_e32 v76, v120
	v_mov_b32_e32 v77, v120
	v_mov_b32_e32 v78, 0
	v_mov_b32_e32 v79, v120
	v_mov_b32_e32 v80, v120
	v_mov_b32_e32 v81, v120
	v_mov_b32_e32 v82, 0
	v_mov_b32_e32 v83, v120
	v_mov_b32_e32 v84, v120
	v_mov_b32_e32 v85, v120
	v_mov_b32_e32 v86, 0
	v_mov_b32_e32 v87, v120
	v_mov_b32_e32 v88, v120
	v_mov_b32_e32 v89, v120
	v_mov_b32_e32 v94, 0
	v_mov_b32_e32 v95, v120
	v_mov_b32_e32 v96, v120
	v_mov_b32_e32 v97, v120
	v_mov_b32_e32 v98, 0
	v_mov_b32_e32 v99, v120
	v_mov_b32_e32 v100, v120
	v_mov_b32_e32 v101, v120
	v_mov_b32_e32 v102, 0
	v_mov_b32_e32 v103, v120
	v_mov_b32_e32 v104, v120
	v_mov_b32_e32 v105, v120
	s_cmpk_lg_i32 s16, 0x800
	s_cselect_b64 s[0:1], -1, 0
	s_cmpk_eq_i32 s16, 0x800
	s_cbranch_scc1 .Lmlas_c1_last
.LBB0_655:
	s_waitcnt vmcnt(6)
	v_mov_b32_e32 v42, v186
	v_mov_b32_e32 v43, v187
	v_mov_b32_e32 v44, v188
	v_mov_b32_e32 v45, v189
	v_mov_b32_e32 v62, v190
	v_mov_b32_e32 v63, v191
	v_mov_b32_e32 v64, v192
	v_mov_b32_e32 v65, v193
	v_mov_b32_e32 v90, v194
	v_mov_b32_e32 v91, v195
	v_mov_b32_e32 v92, v196
	v_mov_b32_e32 v93, v197
	v_mov_b32_e32 v106, v198
	v_mov_b32_e32 v107, v199
	v_mov_b32_e32 v108, v200
	v_mov_b32_e32 v109, v201
	v_add_u32_e32 v210, s16, v128
	v_min_i32_e32 v202, 0x80f, v210
	v_ashrrev_i32_e32 v203, 31, v202
	v_lshlrev_b64 v[202:203], 13, v[202:203]
	v_lshl_add_u64 v[202:203], v[112:113], 0, v[202:203]
	v_min_i32_e32 v204, 0x7ef, v210
	v_ashrrev_i32_e32 v205, 31, v204
	v_lshlrev_b64 v[204:205], 13, v[204:205]
	v_lshl_add_u64 v[204:205], v[112:113], 0, v[204:205]
	v_min_i32_e32 v206, 0x7cf, v210
	v_ashrrev_i32_e32 v207, 31, v206
	v_lshlrev_b64 v[206:207], 13, v[206:207]
	v_lshl_add_u64 v[206:207], v[112:113], 0, v[206:207]
	v_min_i32_e32 v208, 0x7af, v210
	v_ashrrev_i32_e32 v209, 31, v208
	v_lshlrev_b64 v[208:209], 13, v[208:209]
	v_lshl_add_u64 v[208:209], v[112:113], 0, v[208:209]
	v_add_co_u32_e32 v204, vcc, 0x40000, v204
	s_nop 1
	v_addc_co_u32_e32 v205, vcc, 0, v205, vcc
	v_add_co_u32_e32 v206, vcc, s18, v206
	s_nop 1
	v_addc_co_u32_e32 v207, vcc, 0, v207, vcc
	v_add_co_u32_e32 v208, vcc, s48, v208
	s_nop 1
	v_addc_co_u32_e32 v209, vcc, 0, v209, vcc
	global_load_dwordx4 v[186:189], v[202:203], off nt
	global_load_dwordx4 v[190:193], v[204:205], off nt
	global_load_dwordx4 v[194:197], v[206:207], off nt
	global_load_dwordx4 v[198:201], v[208:209], off nt
	v_lshlrev_b32_e32 v139, 16, v43
	v_lshlrev_b32_e32 v138, 16, v42
	v_and_b32_e32 v43, 0xffff0000, v43
	v_and_b32_e32 v42, 0xffff0000, v42
	v_pk_mul_f32 v[140:141], v[42:43], v[42:43]
	v_lshlrev_b32_e32 v143, 16, v45
	v_lshlrev_b32_e32 v142, 16, v44
	v_and_b32_e32 v45, 0xffff0000, v45
	v_and_b32_e32 v44, 0xffff0000, v44
	v_pk_fma_f32 v[140:141], v[138:139], v[138:139], v[140:141]
	v_pk_mul_f32 v[144:145], v[44:45], v[44:45]
	v_add_f32_e32 v3, v140, v141
	v_pk_fma_f32 v[144:145], v[142:143], v[142:143], v[144:145]
	s_nop 0
	v_add_f32_e32 v3, v144, v3
	v_add_f32_e32 v3, v145, v3
	ds_swizzle_b32 v5, v3 offset:swizzle(SWAP,1)
	s_waitcnt lgkmcnt(0)
	v_add_f32_e32 v3, v3, v5
	ds_swizzle_b32 v5, v3 offset:swizzle(SWAP,2)
	s_waitcnt lgkmcnt(0)
	v_add_f32_e32 v3, v3, v5
	ds_swizzle_b32 v5, v3 offset:swizzle(SWAP,4)
	s_waitcnt lgkmcnt(0)
	v_add_f32_e32 v3, v3, v5
	ds_swizzle_b32 v5, v3 offset:swizzle(SWAP,8)
	s_waitcnt lgkmcnt(0)
	v_add_f32_e32 v3, v3, v5
	v_fmamk_f32 v3, v3, 0x3c000000, v246
	v_cmp_gt_f32_e32 vcc, s95, v3
	v_mul_f32_e32 v5, 0x4b800000, v3
	s_nop 0
	v_cndmask_b32_e32 v3, v3, v5, vcc
	v_rsq_f32_e32 v3, v3
	s_nop 0
	v_mul_f32_e32 v5, 0x45800000, v3
	v_cndmask_b32_e32 v3, v3, v5, vcc
	v_mul_f32_e32 v5, v3, v138
	v_mul_f32_e32 v42, v3, v42
	v_mul_f32_e32 v5, v30, v5
	v_mul_f32_e32 v42, v31, v42
	v_cvt_pk_bf16_f32 v42, v5, v42
	v_mul_f32_e32 v5, v3, v139
	v_mul_f32_e32 v43, v3, v43
	v_mul_f32_e32 v5, v32, v5
	v_mul_f32_e32 v43, v33, v43
	v_cvt_pk_bf16_f32 v43, v5, v43
	v_mul_f32_e32 v5, v3, v142
	v_mul_f32_e32 v44, v3, v44
	v_mul_f32_e32 v5, v34, v5
	v_mul_f32_e32 v44, v35, v44
	v_lshlrev_b32_e32 v139, 16, v63
	v_lshlrev_b32_e32 v138, 16, v62
	v_and_b32_e32 v63, 0xffff0000, v63
	v_and_b32_e32 v62, 0xffff0000, v62
	v_cvt_pk_bf16_f32 v44, v5, v44
	v_mul_f32_e32 v5, v3, v143
	v_mul_f32_e32 v3, v3, v45
	v_pk_mul_f32 v[140:141], v[62:63], v[62:63]
	v_lshlrev_b32_e32 v143, 16, v65
	v_lshlrev_b32_e32 v142, 16, v64
	v_and_b32_e32 v65, 0xffff0000, v65
	v_and_b32_e32 v64, 0xffff0000, v64
	v_mul_f32_e32 v3, v37, v3
	v_pk_fma_f32 v[140:141], v[138:139], v[138:139], v[140:141]
	v_pk_mul_f32 v[144:145], v[64:65], v[64:65]
	v_mul_f32_e32 v5, v36, v5
	v_cvt_pk_bf16_f32 v45, v5, v3
	v_pk_fma_f32 v[144:145], v[142:143], v[142:143], v[144:145]
	v_add_f32_e32 v3, v140, v141
	v_add_f32_e32 v3, v144, v3
	v_add_f32_e32 v3, v145, v3
	ds_swizzle_b32 v5, v3 offset:swizzle(SWAP,1)
	s_waitcnt lgkmcnt(0)
	v_add_f32_e32 v3, v3, v5
	ds_swizzle_b32 v5, v3 offset:swizzle(SWAP,2)
	s_waitcnt lgkmcnt(0)
	v_add_f32_e32 v3, v3, v5
	ds_swizzle_b32 v5, v3 offset:swizzle(SWAP,4)
	s_waitcnt lgkmcnt(0)
	v_add_f32_e32 v3, v3, v5
	ds_swizzle_b32 v5, v3 offset:swizzle(SWAP,8)
	s_waitcnt lgkmcnt(0)
	v_add_f32_e32 v3, v3, v5
	v_fmamk_f32 v3, v3, 0x3c000000, v246
	v_cmp_gt_f32_e32 vcc, s95, v3
	v_mul_f32_e32 v5, 0x4b800000, v3
	s_nop 0
	v_cndmask_b32_e32 v3, v3, v5, vcc
	v_rsq_f32_e32 v3, v3
	s_nop 0
	v_mul_f32_e32 v5, 0x45800000, v3
	v_cndmask_b32_e32 v3, v3, v5, vcc
	v_mul_f32_e32 v5, v3, v138
	v_mul_f32_e32 v62, v3, v62
	v_mul_f32_e32 v5, v30, v5
	v_mul_f32_e32 v62, v31, v62
	v_cvt_pk_bf16_f32 v62, v5, v62
	v_mul_f32_e32 v5, v3, v139
	v_mul_f32_e32 v63, v3, v63
	v_mul_f32_e32 v5, v32, v5
	v_mul_f32_e32 v63, v33, v63
	v_cvt_pk_bf16_f32 v63, v5, v63
	v_mul_f32_e32 v5, v3, v142
	v_mul_f32_e32 v64, v3, v64
	v_mul_f32_e32 v5, v34, v5
	v_mul_f32_e32 v64, v35, v64
	v_lshlrev_b32_e32 v139, 16, v91
	v_lshlrev_b32_e32 v138, 16, v90
	v_and_b32_e32 v91, 0xffff0000, v91
	v_and_b32_e32 v90, 0xffff0000, v90
	v_cvt_pk_bf16_f32 v64, v5, v64
	v_mul_f32_e32 v5, v3, v143
	v_mul_f32_e32 v3, v3, v65
	v_pk_mul_f32 v[140:141], v[90:91], v[90:91]
	v_lshlrev_b32_e32 v143, 16, v93
	v_lshlrev_b32_e32 v142, 16, v92
	v_and_b32_e32 v93, 0xffff0000, v93
	v_and_b32_e32 v92, 0xffff0000, v92
	v_mul_f32_e32 v3, v37, v3
	v_pk_fma_f32 v[140:141], v[138:139], v[138:139], v[140:141]
	v_pk_mul_f32 v[144:145], v[92:93], v[92:93]
	v_mul_f32_e32 v5, v36, v5
	v_cvt_pk_bf16_f32 v65, v5, v3
	v_pk_fma_f32 v[144:145], v[142:143], v[142:143], v[144:145]
	v_add_f32_e32 v3, v140, v141
	v_add_f32_e32 v3, v144, v3
	v_add_f32_e32 v3, v145, v3
	ds_swizzle_b32 v5, v3 offset:swizzle(SWAP,1)
	s_waitcnt lgkmcnt(0)
	v_add_f32_e32 v3, v3, v5
	ds_swizzle_b32 v5, v3 offset:swizzle(SWAP,2)
	s_waitcnt lgkmcnt(0)
	v_add_f32_e32 v3, v3, v5
	ds_swizzle_b32 v5, v3 offset:swizzle(SWAP,4)
	s_waitcnt lgkmcnt(0)
	v_add_f32_e32 v3, v3, v5
	ds_swizzle_b32 v5, v3 offset:swizzle(SWAP,8)
	s_waitcnt lgkmcnt(0)
	v_add_f32_e32 v3, v3, v5
	v_fmamk_f32 v3, v3, 0x3c000000, v246
	v_cmp_gt_f32_e32 vcc, s95, v3
	v_mul_f32_e32 v5, 0x4b800000, v3
	s_nop 0
	v_cndmask_b32_e32 v3, v3, v5, vcc
	v_rsq_f32_e32 v3, v3
	s_nop 0
	v_mul_f32_e32 v5, 0x45800000, v3
	v_cndmask_b32_e32 v3, v3, v5, vcc
	v_mul_f32_e32 v5, v3, v138
	v_mul_f32_e32 v90, v3, v90
	v_mul_f32_e32 v5, v30, v5
	v_mul_f32_e32 v90, v31, v90
	v_cvt_pk_bf16_f32 v90, v5, v90
	v_mul_f32_e32 v5, v3, v139
	v_mul_f32_e32 v91, v3, v91
	v_mul_f32_e32 v5, v32, v5
	v_mul_f32_e32 v91, v33, v91
	v_cvt_pk_bf16_f32 v91, v5, v91
	v_mul_f32_e32 v5, v3, v142
	v_mul_f32_e32 v92, v3, v92
	v_mul_f32_e32 v5, v34, v5
	v_mul_f32_e32 v92, v35, v92
	v_lshlrev_b32_e32 v139, 16, v107
	v_lshlrev_b32_e32 v138, 16, v106
	v_and_b32_e32 v107, 0xffff0000, v107
	v_and_b32_e32 v106, 0xffff0000, v106
	v_cvt_pk_bf16_f32 v92, v5, v92
	v_mul_f32_e32 v5, v3, v143
	v_mul_f32_e32 v3, v3, v93
	v_pk_mul_f32 v[140:141], v[106:107], v[106:107]
	v_lshlrev_b32_e32 v143, 16, v109
	v_lshlrev_b32_e32 v142, 16, v108
	v_and_b32_e32 v109, 0xffff0000, v109
	v_and_b32_e32 v108, 0xffff0000, v108
	v_mul_f32_e32 v3, v37, v3
	v_pk_fma_f32 v[140:141], v[138:139], v[138:139], v[140:141]
	v_pk_mul_f32 v[144:145], v[108:109], v[108:109]
	v_mul_f32_e32 v5, v36, v5
	v_cvt_pk_bf16_f32 v93, v5, v3
	v_pk_fma_f32 v[144:145], v[142:143], v[142:143], v[144:145]
	v_add_f32_e32 v3, v140, v141
	v_add_f32_e32 v3, v144, v3
	v_add_f32_e32 v3, v145, v3
	ds_swizzle_b32 v5, v3 offset:swizzle(SWAP,1)
	s_waitcnt lgkmcnt(0)
	v_add_f32_e32 v3, v3, v5
	ds_swizzle_b32 v5, v3 offset:swizzle(SWAP,2)
	s_waitcnt lgkmcnt(0)
	v_add_f32_e32 v3, v3, v5
	ds_swizzle_b32 v5, v3 offset:swizzle(SWAP,4)
	s_waitcnt lgkmcnt(0)
	v_add_f32_e32 v3, v3, v5
	ds_swizzle_b32 v5, v3 offset:swizzle(SWAP,8)
	s_waitcnt lgkmcnt(0)
	v_add_f32_e32 v3, v3, v5
	v_fmamk_f32 v3, v3, 0x3c000000, v246
	v_cmp_gt_f32_e32 vcc, s95, v3
	v_mul_f32_e32 v5, 0x4b800000, v3
	s_nop 0
	v_cndmask_b32_e32 v3, v3, v5, vcc
	v_rsq_f32_e32 v3, v3
	s_nop 0
	v_mul_f32_e32 v5, 0x45800000, v3
	v_cndmask_b32_e32 v3, v3, v5, vcc
	v_mul_f32_e32 v5, v3, v138
	v_mul_f32_e32 v106, v3, v106
	v_mul_f32_e32 v5, v30, v5
	v_mul_f32_e32 v106, v31, v106
	v_cvt_pk_bf16_f32 v106, v5, v106
	v_mul_f32_e32 v5, v3, v139
	v_mul_f32_e32 v107, v3, v107
	v_mul_f32_e32 v5, v32, v5
	v_mul_f32_e32 v107, v33, v107
	v_cvt_pk_bf16_f32 v107, v5, v107
	v_mul_f32_e32 v5, v3, v142
	v_mul_f32_e32 v108, v3, v108
	v_mul_f32_e32 v5, v34, v5
	v_mul_f32_e32 v108, v35, v108
	v_cvt_pk_bf16_f32 v108, v5, v108
	v_mul_f32_e32 v5, v3, v143
	v_mul_f32_e32 v3, v3, v109
	v_mul_f32_e32 v5, v36, v5
	v_mul_f32_e32 v3, v37, v3
	v_cvt_pk_bf16_f32 v109, v5, v3
	s_waitcnt vmcnt(4)
.LBB0_656:
	s_andn2_b64 vcc, exec, s[0:1]
	ds_write_b128 v129, v[42:45]
	ds_write_b128 v130, v[38:41]
	ds_write_b128 v129, v[62:65] offset:12288
	ds_write_b128 v130, v[46:49] offset:8192
	ds_write_b128 v129, v[90:93] offset:24576
	ds_write_b128 v130, v[50:53] offset:16384
	ds_write_b128 v129, v[106:109] offset:36864
	ds_write_b128 v130, v[54:57] offset:24576
	ds_write_b128 v131, v[58:61] offset:256
	ds_write_b128 v131, v[66:69] offset:24832
	s_waitcnt lgkmcnt(0)
	s_barrier
	s_cbranch_vccnz .LBB0_658
	v_add_u32_e32 v3, s16, v128
	v_min_i32_e32 v46, 0x7ef, v3
	v_ashrrev_i32_e32 v47, 31, v46
	v_lshlrev_b64 v[46:47], 13, v[46:47]
	v_min_i32_e32 v50, 0x7cf, v3
	v_lshl_add_u64 v[46:47], v[112:113], 0, v[46:47]
	v_ashrrev_i32_e32 v51, 31, v50
	v_lshl_add_u64 v[48:49], v[46:47], 0, s[4:5]
	v_add_co_u32_e32 v46, vcc, 0x40000, v46
	v_lshlrev_b64 v[50:51], 13, v[50:51]
	v_min_i32_e32 v54, 0x7af, v3
	v_min_i32_e32 v38, 0x80f, v3
	v_addc_co_u32_e32 v47, vcc, 0, v47, vcc
	v_lshl_add_u64 v[50:51], v[112:113], 0, v[50:51]
	v_ashrrev_i32_e32 v55, 31, v54
	v_add_u32_e32 v3, s16, v127
	v_lshl_add_u64 v[52:53], v[50:51], 0, s[96:97]
	v_add_co_u32_e32 v50, vcc, s18, v50
	v_lshlrev_b64 v[54:55], 13, v[54:55]
	v_min_i32_e32 v60, 0x7cf, v3
	v_addc_co_u32_e32 v51, vcc, 0, v51, vcc
	v_lshl_add_u64 v[54:55], v[112:113], 0, v[54:55]
	s_mov_b64 s[0:1], 0xc0000
	v_ashrrev_i32_e32 v61, 31, v60
	v_lshl_add_u64 v[56:57], v[54:55], 0, s[0:1]
	v_add_co_u32_e32 v54, vcc, s48, v54
	v_min_i32_e32 v58, 0x80f, v3
	v_lshlrev_b64 v[60:61], 7, v[60:61]
	v_ashrrev_i32_e32 v39, 31, v38
	v_addc_co_u32_e32 v55, vcc, 0, v55, vcc
	v_ashrrev_i32_e32 v59, 31, v58
	v_lshl_add_u64 v[60:61], v[114:115], 0, v[60:61]
	v_lshlrev_b64 v[38:39], 13, v[38:39]
	v_lshlrev_b64 v[58:59], 7, v[58:59]
	v_add_co_u32_e32 v66, vcc, s88, v60
	v_lshl_add_u64 v[38:39], v[112:113], 0, v[38:39]
	v_lshl_add_u64 v[58:59], v[114:115], 0, v[58:59]
	v_addc_co_u32_e32 v67, vcc, 0, v61, vcc
	s_nop 0
	global_load_dwordx4 v[38:41], v[38:39], off offset:256 nt
	s_nop 0
	s_nop 0
	global_load_dwordx4 v[46:49], v[48:49], off offset:256 nt
	s_nop 0
	s_nop 0
	global_load_dwordx4 v[50:53], v[52:53], off offset:256 nt
	s_nop 0
	s_nop 0
	global_load_dwordx4 v[54:57], v[56:57], off offset:256 nt
	s_nop 0
	global_load_dwordx4 v[58:61], v[58:59], off
	s_nop 0
	global_load_dwordx4 v[66:69], v[66:67], off

.Lmlas_c1_last:
	s_waitcnt vmcnt(0)
	v_mov_b32_e32 v42, v186
	v_mov_b32_e32 v43, v187
	v_mov_b32_e32 v44, v188
	v_mov_b32_e32 v45, v189
	v_mov_b32_e32 v62, v190
	v_mov_b32_e32 v63, v191
	v_mov_b32_e32 v64, v192
	v_mov_b32_e32 v65, v193
	v_mov_b32_e32 v90, v194
	v_mov_b32_e32 v91, v195
	v_mov_b32_e32 v92, v196
	v_mov_b32_e32 v93, v197
	v_mov_b32_e32 v106, v198
	v_mov_b32_e32 v107, v199
	v_mov_b32_e32 v108, v200
	v_mov_b32_e32 v109, v201
	s_branch .LBB0_656
